# xp tiles last + all blocks run pooling pre-pass first (original item distribution)
# baseline (speedup 1.0000x reference)
; #define OPAQUE_TID() int tid = threadIdx.x; asm volatile("" : "+v"(tid)); const int lane = tid & 63, wave = __builtin_amdgcn_readfirstlane(tid >> 6); (void)lane; (void)wave
; __device__ __forceinline__ void pool_prepass(const Args& a) {
;     OPAQUE_TID();
;     const bf16_t* U = (const bf16_t*)(a.ws + WS_U);
;     bf16_t* PB = (bf16_t*)a.out;
;     const int G = gridDim.x, gq = wave & 3, ch = gq * 256 + (lane & 31) * 8;
;     for (int it = blockIdx.x; it < MT / 64; it += G) {
;         const int row0 = (it * 4 + (wave >> 2) * 2 + (lane >> 5)) * 16;
;         if (gq == 0) pool_run<2>(a, U, PB, row0, ch);
;         else if (gq == 1) pool_run<4>(a, U, PB, row0, ch);
;         else if (gq == 2) pool_run<8>(a, U, PB, row0, ch);
;         else pool_run<16>(a, U, PB, row0, ch);
;     }
; __global__ void __launch_bounds__(512, 2) fwd_megakernel(Args a) {
;     ...
;         if ((bid >> 5) & 1) pool_prepass(a);
.LBB0_341:
	s_or_b64 exec, exec, s[0:1]
	s_bitcmp0_b32 s2, 5
	s_cselect_b64 s[40:41], -1, 0
	s_and_b64 vcc, exec, s[40:41]
	s_waitcnt lgkmcnt(0)
	s_barrier
	v_mov_b32_e32 v0, v180
	s_cmpk_gt_i32 s2, 0x20f
	v_readfirstlane_b32 s0, v0
	s_cbranch_scc1 .LBB0_642
	v_lshlrev_b32_e32 v1, 3, v0
	s_bfe_u32 s12, s0, 0x20006
	v_and_b32_e32 v1, 0xf8, v1
	s_ashr_i32 s0, s0, 7
	v_lshl_or_b32 v124, s12, 8, v1
	s_and_b32 s0, s0, -2
	s_lshl_b32 s1, s2, 2
	v_bfe_u32 v125, v0, 5, 1
	v_mov_b32_e32 v127, 0
	v_lshlrev_b32_e32 v126, 1, v124
	s_add_i32 s13, s1, s0
	v_lshl_add_u64 v[128:129], s[28:29], 0, v[126:127]
	v_lshl_add_u64 v[130:131], s[26:27], 0, v[126:127]
	v_lshlrev_b32_e32 v126, 2, v124
	v_or_b32_e32 v0, s13, v125
	v_lshl_add_u64 v[132:133], s[44:45], 0, v[126:127]
	s_lshl_b32 s14, s30, 2
	v_lshl_or_b32 v134, v0, 4, 15
	s_lshl_b32 s15, s30, 6
	s_movk_i32 s42, 0x7ff
	v_mov_b32_e32 v139, 0xfffff80f
	v_not_b32_e32 v170, 16
	v_mov_b32_e32 v171, 0x7ff
	s_movk_i32 s43, 0x3800
	s_mov_b32 s52, 0x3d800000
	s_mov_b32 s53, 0x3e000000
	s_mov_b32 s54, 0x3e800000
	v_mov_b32_e32 v172, 0x7f1
	v_mov_b32_e32 v173, 0x2100000
	v_mov_b32_e32 v174, 0x2540040
	v_mov_b32_e32 v175, 0x41800000
	v_mov_b32_e32 v176, 0x41000000
	s_mov_b32 s55, s2
	s_branch .LBB0_345
